# phase B epilogue row-scale loads prefetched (gate tiles one group ahead, head tiles all at once); phase E static priority raise removed (no measurable effect)
# speedup vs baseline: 1.0185x; 1.0087x over previous
; __device__ __forceinline__ unsigned gq8(float x) { return (unsigned)(sigmoidf_(x) * 255.0f + 0.5f); }
;     __device__ __forceinline__ void operator()(const f32x4 (&acc)[2][2][4][2], const pg8::Unit& u, int wr, int wc, int fr_, int fq_) const {
;     ...
; #pragma unroll
;             for (int ai = 0; ai < 2; ++ai)
; #pragma unroll
;                 for (int m = 0; m < 4; ++m) { const unsigned row = (unsigned)(u.pm * 256 + 128 * ai + 64 * wr + 16 * m + fr);
;                     const float rin = rsq ? __builtin_amdgcn_rsqf(rsq[row] * (1.0f / DM) + 1e-6f) : 1.0f;
; #pragma unroll
;                     for (int bj = 0; bj < 2; ++bj) { const f32x4 a0 = acc[ai][bj][m][0] * rin, a1 = acc[ai][bj][m][1] * rin; u32x2 w;
;                         w.x = gq8(a0[0]) | (gq8(a0[1]) << 8) | (gq8(a0[2]) << 16) | (gq8(a0[3]) << 24);
;                         w.y = gq8(a1[0]) | (gq8(a1[1]) << 8) | (gq8(a1[2]) << 16) | (gq8(a1[3]) << 24);
;                         *(u32x2*)((unsigned char*)brg + (row * 3072u + (unsigned)((t - 12) * 256 + 64 * wc + 32 * bj + 8 * fq))) = w; } }
.LBB0_437:
	v_mov_b32_e32 v142, v153
	v_mov_b32_e32 v157, v154
	s_cmp_gt_i32 s36, 10
	s_mov_b64 s[6:7], -1
	s_cbranch_scc0 .LBB0_477
	s_cmp_eq_u32 s36, 11
	s_cbranch_scc1 .LBB0_456
	s_lshl_b32 s6, s38, 8
	s_add_i32 s6, s6, s64
	v_add_u32_e32 v80, s6, v142
	v_mov_b32_e32 v138, 1.0
	s_and_b64 vcc, exec, s[8:9]
	v_mov_b32_e32 v140, 1.0
	s_cbranch_vccz .LBB0_441
	v_lshl_add_u64 v[140:141], v[80:81], 2, s[14:15]
	v_mov_b32_e32 v252, v140
	v_mov_b32_e32 v253, v141
	global_load_dword v250, v[252:253], off
	global_load_dword v251, v[252:253], off offset:64
	s_waitcnt vmcnt(1)
	v_mov_b32_e32 v139, v250
	v_fmamk_f32 v139, v139, 0x3a800000, v147
	v_rsq_f32_e32 v140, v139
.LBB0_441:
	v_mul_lo_u32 v141, v80, s74
	v_pk_mul_f32 v[158:159], v[126:127], v[140:141] op_sel_hi:[1,0]
	v_pk_mul_f32 v[144:145], v[128:129], v[140:141] op_sel_hi:[1,0]
	v_mul_f32_e32 v152, 0xbfb8aa3b, v158
	v_exp_f32_e32 v152, v152
	v_mul_f32_e32 v158, 0xbfb8aa3b, v159
	v_exp_f32_e32 v163, v158
	v_mul_f32_e32 v144, 0xbfb8aa3b, v144
	v_add_f32_e32 v152, 1.0, v152
	v_rcp_f32_e32 v162, v152
	v_add_f32_e32 v152, 1.0, v163
	v_exp_f32_e32 v163, v144
	v_mul_f32_e32 v144, 0xbfb8aa3b, v145
	v_pk_mul_f32 v[158:159], v[122:123], v[140:141] op_sel_hi:[1,0]
	v_exp_f32_e32 v145, v144
	v_rcp_f32_e32 v144, v152
	v_add_f32_e32 v152, 1.0, v163
	v_rcp_f32_e32 v170, v152
	v_mul_f32_e32 v152, 0xbfb8aa3b, v158
	v_exp_f32_e32 v152, v152
	v_mul_f32_e32 v158, 0xbfb8aa3b, v159
	v_exp_f32_e32 v159, v158
	v_add_f32_e32 v145, 1.0, v145
	v_pk_mul_f32 v[160:161], v[124:125], v[140:141] op_sel_hi:[1,0]
	v_rcp_f32_e32 v158, v145
	v_add_f32_e32 v145, 1.0, v152
	v_rcp_f32_e32 v163, v145
	v_add_f32_e32 v145, 1.0, v159
	v_mul_f32_e32 v152, 0xbfb8aa3b, v160
	v_exp_f32_e32 v152, v152
	v_mul_f32_e32 v159, 0xbfb8aa3b, v161
	v_rcp_f32_e32 v145, v145
	s_lshl_b32 s6, s36, 8
	v_exp_f32_e32 v159, v159
	s_add_i32 s6, s67, s6
	v_lshl_add_u32 v139, v157, 3, s6
	s_mov_b32 s6, 0x437f0000
	v_add_f32_e32 v152, 1.0, v152
	v_pk_fma_f32 v[144:145], v[144:145], s[6:7], 0.5 op_sel_hi:[1,0,0]
	v_rcp_f32_e32 v171, v152
	v_add_f32_e32 v152, 1.0, v159
	v_pk_fma_f32 v[160:161], v[162:163], s[6:7], 0.5 op_sel_hi:[1,0,0]
	v_cvt_u32_f32_e32 v145, v145
	v_cvt_u32_f32_e32 v144, v144
	v_rcp_f32_e32 v159, v152
	v_cvt_u32_f32_e32 v152, v161
	v_cvt_u32_f32_e32 v160, v160
	v_lshlrev_b32_e32 v145, 8, v145
	v_lshlrev_b32_e32 v144, 8, v144
	v_or_b32_e32 v152, v145, v152
	v_or_b32_e32 v160, v144, v160
	v_pk_fma_f32 v[144:145], v[170:171], s[6:7], 0.5 op_sel_hi:[1,0,0]
	v_add_u32_e32 v143, v141, v139
	v_cvt_u32_f32_sdwa v161, v144 dst_sel:WORD_1 dst_unused:UNUSED_PAD src0_sel:DWORD
	v_cvt_u32_f32_sdwa v162, v145 dst_sel:WORD_1 dst_unused:UNUSED_PAD src0_sel:DWORD
	v_pk_fma_f32 v[144:145], v[158:159], s[6:7], 0.5 op_sel_hi:[1,0,0]
	s_andn2_b64 vcc, exec, s[8:9]
	v_cvt_u32_f32_sdwa v144, v144 dst_sel:BYTE_3 dst_unused:UNUSED_PAD src0_sel:DWORD
	v_cvt_u32_f32_sdwa v145, v145 dst_sel:BYTE_3 dst_unused:UNUSED_PAD src0_sel:DWORD
	v_or_b32_e32 v158, v160, v161
	v_or_b32_e32 v152, v152, v162
	v_or_b32_e32 v144, v158, v144
	v_pk_mul_f32 v[158:159], v[118:119], v[140:141] op_sel_hi:[1,0]
	v_or_b32_e32 v145, v152, v145
	v_mul_f32_e32 v152, 0xbfb8aa3b, v158
	v_exp_f32_e32 v152, v152
	global_store_dwordx2 v143, v[144:145], s[22:23]
	v_pk_mul_f32 v[144:145], v[120:121], v[140:141] op_sel_hi:[1,0]
	v_mul_f32_e32 v158, 0xbfb8aa3b, v159
	v_exp_f32_e32 v163, v158
	v_mul_f32_e32 v144, 0xbfb8aa3b, v144
	v_pk_mul_f32 v[160:161], v[116:117], v[140:141] op_sel_hi:[1,0]
	v_pk_mul_f32 v[158:159], v[114:115], v[140:141] op_sel_hi:[1,0]
	v_add_f32_e32 v140, 1.0, v152
	v_exp_f32_e32 v152, v144
	v_mul_f32_e32 v144, 0xbfb8aa3b, v145
	v_exp_f32_e32 v145, v144
	v_rcp_f32_e32 v162, v140
	v_add_f32_e32 v140, 1.0, v163
	v_rcp_f32_e32 v144, v140
	v_add_f32_e32 v140, 1.0, v152
	v_rcp_f32_e32 v170, v140
	v_add_f32_e32 v140, 1.0, v145
	v_mul_f32_e32 v145, 0xbfb8aa3b, v158
	v_exp_f32_e32 v145, v145
	v_mul_f32_e32 v152, 0xbfb8aa3b, v159
	v_exp_f32_e32 v152, v152
	v_rcp_f32_e32 v158, v140
	v_add_f32_e32 v140, 1.0, v145
	v_mul_f32_e32 v145, 0xbfb8aa3b, v160
	v_rcp_f32_e32 v163, v140
	v_add_f32_e32 v140, 1.0, v152
	v_exp_f32_e32 v152, v145
	v_mul_f32_e32 v145, 0xbfb8aa3b, v161
	v_exp_f32_e32 v159, v145
	v_rcp_f32_e32 v145, v140
	v_add_f32_e32 v140, 1.0, v152
	v_rcp_f32_e32 v171, v140
	v_add_f32_e32 v140, 1.0, v159
	v_pk_fma_f32 v[144:145], v[144:145], s[6:7], 0.5 op_sel_hi:[1,0,0]
	v_rcp_f32_e32 v159, v140
	v_pk_fma_f32 v[160:161], v[162:163], s[6:7], 0.5 op_sel_hi:[1,0,0]
	v_cvt_u32_f32_e32 v140, v145
	v_cvt_u32_f32_e32 v144, v144
	v_cvt_u32_f32_e32 v145, v161
	v_cvt_u32_f32_e32 v152, v160
	v_lshlrev_b32_e32 v140, 8, v140
	v_lshlrev_b32_e32 v144, 8, v144
	v_or_b32_e32 v140, v140, v145
	v_or_b32_e32 v152, v144, v152
	v_pk_fma_f32 v[144:145], v[170:171], s[6:7], 0.5 op_sel_hi:[1,0,0]
	s_nop 0
	v_cvt_u32_f32_sdwa v160, v144 dst_sel:WORD_1 dst_unused:UNUSED_PAD src0_sel:DWORD
	v_cvt_u32_f32_sdwa v161, v145 dst_sel:WORD_1 dst_unused:UNUSED_PAD src0_sel:DWORD
	v_pk_fma_f32 v[144:145], v[158:159], s[6:7], 0.5 op_sel_hi:[1,0,0]
	v_or_b32_e32 v152, v152, v160
	v_cvt_u32_f32_sdwa v145, v145 dst_sel:BYTE_3 dst_unused:UNUSED_PAD src0_sel:DWORD
	v_cvt_u32_f32_sdwa v144, v144 dst_sel:BYTE_3 dst_unused:UNUSED_PAD src0_sel:DWORD
	v_or_b32_e32 v140, v140, v161
	v_or_b32_e32 v145, v140, v145
	v_add_u32_e32 v140, 32, v143
	v_cndmask_b32_e64 v143, 0, 1, s[8:9]
	v_or_b32_e32 v144, v152, v144
	v_cmp_ne_u32_e64 s[6:7], 1, v143
	global_store_dwordx2 v140, v[144:145], s[22:23]
	s_cbranch_vccnz .LBB0_443
	v_add_u32_e32 v144, 16, v80
	v_mov_b32_e32 v145, v81
	v_lshl_add_u64 v[144:145], v[144:145], 2, s[14:15]
	global_load_dword v250, v[252:253], off offset:128
	s_waitcnt vmcnt(3)
	v_mov_b32_e32 v138, v251
	v_fmamk_f32 v138, v138, 0x3a800000, v147
	v_rsq_f32_e32 v138, v138
; __device__ __forceinline__ unsigned gq8(float x) { return (unsigned)(sigmoidf_(x) * 255.0f + 0.5f); }
;     __device__ __forceinline__ void operator()(const f32x4 (&acc)[2][2][4][2], const pg8::Unit& u, int wr, int wc, int fr_, int fq_) const {
;     ...
; #pragma unroll
;             for (int ai = 0; ai < 2; ++ai)
; #pragma unroll
;                 for (int m = 0; m < 4; ++m) { const unsigned row = (unsigned)(u.pm * 256 + 128 * ai + 64 * wr + 16 * m + fr);
;                     const float rin = rsq ? __builtin_amdgcn_rsqf(rsq[row] * (1.0f / DM) + 1e-6f) : 1.0f;
; #pragma unroll
;                     for (int bj = 0; bj < 2; ++bj) { const f32x4 a0 = acc[ai][bj][m][0] * rin, a1 = acc[ai][bj][m][1] * rin; u32x2 w;
;                         w.x = gq8(a0[0]) | (gq8(a0[1]) << 8) | (gq8(a0[2]) << 16) | (gq8(a0[3]) << 24);
;                         w.y = gq8(a1[0]) | (gq8(a1[1]) << 8) | (gq8(a1[2]) << 16) | (gq8(a1[3]) << 24);
;                         *(u32x2*)((unsigned char*)brg + (row * 3072u + (unsigned)((t - 12) * 256 + 64 * wc + 32 * bj + 8 * fq))) = w; } }
.LBB0_443:
	s_nop 0
	v_pk_mul_f32 v[158:159], v[110:111], v[138:139] op_sel_hi:[1,0]
	v_pk_mul_f32 v[144:145], v[112:113], v[138:139] op_sel_hi:[1,0]
	v_mul_f32_e32 v143, 0xbfb8aa3b, v158
	v_exp_f32_e32 v143, v143
	v_mul_f32_e32 v152, 0xbfb8aa3b, v159
	v_exp_f32_e32 v152, v152
	v_mul_f32_e32 v144, 0xbfb8aa3b, v144
	v_add_f32_e32 v143, 1.0, v143
	v_rcp_f32_e32 v162, v143
	v_add_f32_e32 v143, 1.0, v152
	v_exp_f32_e32 v152, v144
	v_mul_f32_e32 v144, 0xbfb8aa3b, v145
	v_exp_f32_e32 v145, v144
	v_pk_mul_f32 v[158:159], v[106:107], v[138:139] op_sel_hi:[1,0]
	v_rcp_f32_e32 v144, v143
	v_add_f32_e32 v143, 1.0, v152
	v_rcp_f32_e32 v170, v143
	v_add_f32_e32 v143, 1.0, v145
	v_mul_f32_e32 v145, 0xbfb8aa3b, v158
	v_exp_f32_e32 v145, v145
	v_mul_f32_e32 v152, 0xbfb8aa3b, v159
	v_exp_f32_e32 v152, v152
	v_pk_mul_f32 v[160:161], v[108:109], v[138:139] op_sel_hi:[1,0]
	v_rcp_f32_e32 v158, v143
	v_add_f32_e32 v143, 1.0, v145
	v_mul_f32_e32 v145, 0xbfb8aa3b, v160
	v_rcp_f32_e32 v163, v143
	v_add_f32_e32 v143, 1.0, v152
	v_exp_f32_e32 v152, v145
	v_mul_f32_e32 v145, 0xbfb8aa3b, v161
	v_exp_f32_e32 v159, v145
	v_rcp_f32_e32 v145, v143
	v_add_f32_e32 v143, 1.0, v152
	s_mov_b32 s30, 0x437f0000
	v_rcp_f32_e32 v171, v143
	v_add_f32_e32 v143, 1.0, v159
	v_pk_fma_f32 v[144:145], v[144:145], s[30:31], 0.5 op_sel_hi:[1,0,0]
	v_rcp_f32_e32 v159, v143
	v_pk_fma_f32 v[160:161], v[162:163], s[30:31], 0.5 op_sel_hi:[1,0,0]
	v_cvt_u32_f32_e32 v143, v145
	v_cvt_u32_f32_e32 v144, v144
	v_cvt_u32_f32_e32 v145, v161
	v_cvt_u32_f32_e32 v152, v160
	v_lshlrev_b32_e32 v143, 8, v143
	v_lshlrev_b32_e32 v144, 8, v144
	v_or_b32_e32 v143, v143, v145
	v_or_b32_e32 v152, v144, v152
	v_pk_fma_f32 v[144:145], v[170:171], s[30:31], 0.5 op_sel_hi:[1,0,0]
	v_add_u32_e32 v141, 0xc000, v141
	v_cvt_u32_f32_sdwa v160, v144 dst_sel:WORD_1 dst_unused:UNUSED_PAD src0_sel:DWORD
	v_cvt_u32_f32_sdwa v161, v145 dst_sel:WORD_1 dst_unused:UNUSED_PAD src0_sel:DWORD
	v_pk_fma_f32 v[144:145], v[158:159], s[30:31], 0.5 op_sel_hi:[1,0,0]
	v_pk_mul_f32 v[158:159], v[102:103], v[138:139] op_sel_hi:[1,0]
	v_cvt_u32_f32_sdwa v145, v145 dst_sel:BYTE_3 dst_unused:UNUSED_PAD src0_sel:DWORD
	v_cvt_u32_f32_sdwa v144, v144 dst_sel:BYTE_3 dst_unused:UNUSED_PAD src0_sel:DWORD
	v_or_b32_e32 v143, v143, v161
	v_or_b32_e32 v152, v152, v160
	v_or_b32_e32 v145, v143, v145
	v_mul_f32_e32 v143, 0xbfb8aa3b, v158
	v_exp_f32_e32 v143, v143
	v_add_u32_e32 v140, v141, v139
	v_or_b32_e32 v144, v152, v144
	global_store_dwordx2 v140, v[144:145], s[22:23]
	v_pk_mul_f32 v[144:145], v[104:105], v[138:139] op_sel_hi:[1,0]
	v_mul_f32_e32 v152, 0xbfb8aa3b, v159
	v_pk_mul_f32 v[160:161], v[100:101], v[138:139] op_sel_hi:[1,0]
	v_exp_f32_e32 v152, v152
	v_pk_mul_f32 v[158:159], v[98:99], v[138:139] op_sel_hi:[1,0]
	v_add_f32_e32 v138, 1.0, v143
	v_mul_f32_e32 v143, 0xbfb8aa3b, v144
	v_exp_f32_e32 v143, v143
	v_mul_f32_e32 v144, 0xbfb8aa3b, v145
	v_exp_f32_e32 v145, v144
	v_rcp_f32_e32 v162, v138
	v_add_f32_e32 v138, 1.0, v152
	v_rcp_f32_e32 v144, v138
	v_add_f32_e32 v138, 1.0, v143
	v_mul_f32_e32 v143, 0xbfb8aa3b, v158
	v_rcp_f32_e32 v170, v138
	v_add_f32_e32 v138, 1.0, v145
	v_exp_f32_e32 v143, v143
	v_mul_f32_e32 v145, 0xbfb8aa3b, v159
	v_exp_f32_e32 v145, v145
	v_rcp_f32_e32 v158, v138
	v_add_f32_e32 v138, 1.0, v143
	v_mul_f32_e32 v143, 0xbfb8aa3b, v160
	v_rcp_f32_e32 v163, v138
	v_add_f32_e32 v138, 1.0, v145
	v_exp_f32_e32 v143, v143
	v_mul_f32_e32 v145, 0xbfb8aa3b, v161
	v_exp_f32_e32 v152, v145
	v_rcp_f32_e32 v145, v138
	v_add_f32_e32 v138, 1.0, v143
	v_rcp_f32_e32 v171, v138
	v_add_f32_e32 v138, 1.0, v152
	v_pk_fma_f32 v[144:145], v[144:145], s[30:31], 0.5 op_sel_hi:[1,0,0]
	v_rcp_f32_e32 v159, v138
	v_pk_fma_f32 v[160:161], v[162:163], s[30:31], 0.5 op_sel_hi:[1,0,0]
	v_cvt_u32_f32_e32 v138, v145
	v_cvt_u32_f32_e32 v143, v144
	v_cvt_u32_f32_e32 v144, v161
	v_cvt_u32_f32_e32 v145, v160
	v_lshlrev_b32_e32 v138, 8, v138
	v_lshlrev_b32_e32 v143, 8, v143
	v_or_b32_e32 v138, v138, v144
	v_or_b32_e32 v143, v143, v145
	v_pk_fma_f32 v[144:145], v[170:171], s[30:31], 0.5 op_sel_hi:[1,0,0]
	s_and_b64 vcc, exec, s[6:7]
	v_cvt_u32_f32_sdwa v152, v144 dst_sel:WORD_1 dst_unused:UNUSED_PAD src0_sel:DWORD
	v_cvt_u32_f32_sdwa v160, v145 dst_sel:WORD_1 dst_unused:UNUSED_PAD src0_sel:DWORD
	v_pk_fma_f32 v[144:145], v[158:159], s[30:31], 0.5 op_sel_hi:[1,0,0]
	v_or_b32_e32 v143, v143, v152
	v_cvt_u32_f32_sdwa v145, v145 dst_sel:BYTE_3 dst_unused:UNUSED_PAD src0_sel:DWORD
	v_cvt_u32_f32_sdwa v144, v144 dst_sel:BYTE_3 dst_unused:UNUSED_PAD src0_sel:DWORD
	v_or_b32_e32 v138, v138, v160
	v_or_b32_e32 v145, v138, v145
	v_or_b32_e32 v144, v143, v144
	v_add_u32_e32 v138, 32, v140
	global_store_dwordx2 v138, v[144:145], s[22:23]
	v_mov_b32_e32 v138, 1.0
	v_mov_b32_e32 v140, 1.0
	s_cbranch_vccnz .LBB0_445
	v_add_u32_e32 v144, 32, v80
	v_mov_b32_e32 v145, v81
	v_lshl_add_u64 v[144:145], v[144:145], 2, s[14:15]
	global_load_dword v251, v[252:253], off offset:192
	s_waitcnt vmcnt(3)
	v_mov_b32_e32 v140, v250
	v_fmamk_f32 v140, v140, 0x3a800000, v147
	v_rsq_f32_e32 v140, v140
; __device__ __forceinline__ unsigned gq8(float x) { return (unsigned)(sigmoidf_(x) * 255.0f + 0.5f); }
;     __device__ __forceinline__ void operator()(const f32x4 (&acc)[2][2][4][2], const pg8::Unit& u, int wr, int wc, int fr_, int fq_) const {
;     ...
; #pragma unroll
;             for (int ai = 0; ai < 2; ++ai)
; #pragma unroll
;                 for (int m = 0; m < 4; ++m) { const unsigned row = (unsigned)(u.pm * 256 + 128 * ai + 64 * wr + 16 * m + fr);
;                     const float rin = rsq ? __builtin_amdgcn_rsqf(rsq[row] * (1.0f / DM) + 1e-6f) : 1.0f;
; #pragma unroll
;                     for (int bj = 0; bj < 2; ++bj) { const f32x4 a0 = acc[ai][bj][m][0] * rin, a1 = acc[ai][bj][m][1] * rin; u32x2 w;
;                         w.x = gq8(a0[0]) | (gq8(a0[1]) << 8) | (gq8(a0[2]) << 16) | (gq8(a0[3]) << 24);
;                         w.y = gq8(a1[0]) | (gq8(a1[1]) << 8) | (gq8(a1[2]) << 16) | (gq8(a1[3]) << 24);
;                         *(u32x2*)((unsigned char*)brg + (row * 3072u + (unsigned)((t - 12) * 256 + 64 * wc + 32 * bj + 8 * fq))) = w; } }
.LBB0_445:
	v_add_u32_e32 v141, 0xc000, v141
	v_pk_mul_f32 v[158:159], v[94:95], v[140:141] op_sel_hi:[1,0]
	v_pk_mul_f32 v[144:145], v[96:97], v[140:141] op_sel_hi:[1,0]
	v_mul_f32_e32 v152, 0xbfb8aa3b, v158
	v_exp_f32_e32 v152, v152
	v_mul_f32_e32 v158, 0xbfb8aa3b, v159
	v_exp_f32_e32 v163, v158
	v_mul_f32_e32 v144, 0xbfb8aa3b, v144
	v_add_f32_e32 v152, 1.0, v152
	v_rcp_f32_e32 v162, v152
	v_add_f32_e32 v152, 1.0, v163
	v_exp_f32_e32 v163, v144
	v_mul_f32_e32 v144, 0xbfb8aa3b, v145
	v_pk_mul_f32 v[158:159], v[90:91], v[140:141] op_sel_hi:[1,0]
	v_exp_f32_e32 v145, v144
	v_rcp_f32_e32 v144, v152
	v_add_f32_e32 v152, 1.0, v163
	v_rcp_f32_e32 v170, v152
	v_mul_f32_e32 v152, 0xbfb8aa3b, v158
	v_exp_f32_e32 v152, v152
	v_mul_f32_e32 v158, 0xbfb8aa3b, v159
	v_exp_f32_e32 v159, v158
	v_add_f32_e32 v145, 1.0, v145
	v_pk_mul_f32 v[160:161], v[92:93], v[140:141] op_sel_hi:[1,0]
	v_rcp_f32_e32 v158, v145
	v_add_f32_e32 v145, 1.0, v152
	v_rcp_f32_e32 v163, v145
	v_add_f32_e32 v145, 1.0, v159
	v_mul_f32_e32 v152, 0xbfb8aa3b, v160
	v_exp_f32_e32 v152, v152
	v_mul_f32_e32 v159, 0xbfb8aa3b, v161
	v_rcp_f32_e32 v145, v145
	v_exp_f32_e32 v159, v159
	v_add_f32_e32 v152, 1.0, v152
	v_rcp_f32_e32 v171, v152
	v_pk_fma_f32 v[144:145], v[144:145], s[30:31], 0.5 op_sel_hi:[1,0,0]
	v_add_f32_e32 v152, 1.0, v159
	v_pk_fma_f32 v[160:161], v[162:163], s[30:31], 0.5 op_sel_hi:[1,0,0]
	v_cvt_u32_f32_e32 v145, v145
	v_cvt_u32_f32_e32 v144, v144
	v_rcp_f32_e32 v159, v152
	v_cvt_u32_f32_e32 v152, v161
	v_cvt_u32_f32_e32 v160, v160
	v_lshlrev_b32_e32 v145, 8, v145
	v_lshlrev_b32_e32 v144, 8, v144
	v_or_b32_e32 v152, v145, v152
	v_or_b32_e32 v160, v144, v160
	v_pk_fma_f32 v[144:145], v[170:171], s[30:31], 0.5 op_sel_hi:[1,0,0]
	v_add_u32_e32 v143, v141, v139
	v_cvt_u32_f32_sdwa v161, v144 dst_sel:WORD_1 dst_unused:UNUSED_PAD src0_sel:DWORD
	v_cvt_u32_f32_sdwa v162, v145 dst_sel:WORD_1 dst_unused:UNUSED_PAD src0_sel:DWORD
	v_pk_fma_f32 v[144:145], v[158:159], s[30:31], 0.5 op_sel_hi:[1,0,0]
	s_and_b64 vcc, exec, s[6:7]
	v_cvt_u32_f32_sdwa v144, v144 dst_sel:BYTE_3 dst_unused:UNUSED_PAD src0_sel:DWORD
	v_cvt_u32_f32_sdwa v145, v145 dst_sel:BYTE_3 dst_unused:UNUSED_PAD src0_sel:DWORD
	v_or_b32_e32 v158, v160, v161
	v_or_b32_e32 v152, v152, v162
	v_or_b32_e32 v144, v158, v144
	v_pk_mul_f32 v[158:159], v[86:87], v[140:141] op_sel_hi:[1,0]
	v_or_b32_e32 v145, v152, v145
	v_mul_f32_e32 v152, 0xbfb8aa3b, v158
	v_exp_f32_e32 v152, v152
	global_store_dwordx2 v143, v[144:145], s[22:23]
	v_pk_mul_f32 v[144:145], v[88:89], v[140:141] op_sel_hi:[1,0]
	v_mul_f32_e32 v158, 0xbfb8aa3b, v159
	v_exp_f32_e32 v163, v158
	v_mul_f32_e32 v144, 0xbfb8aa3b, v144
	v_pk_mul_f32 v[160:161], v[84:85], v[140:141] op_sel_hi:[1,0]
	v_pk_mul_f32 v[158:159], v[82:83], v[140:141] op_sel_hi:[1,0]
	v_add_f32_e32 v140, 1.0, v152
	v_exp_f32_e32 v152, v144
	v_mul_f32_e32 v144, 0xbfb8aa3b, v145
	v_exp_f32_e32 v145, v144
	v_rcp_f32_e32 v162, v140
	v_add_f32_e32 v140, 1.0, v163
	v_rcp_f32_e32 v144, v140
	v_add_f32_e32 v140, 1.0, v152
	v_rcp_f32_e32 v170, v140
	v_add_f32_e32 v140, 1.0, v145
	v_mul_f32_e32 v145, 0xbfb8aa3b, v158
	v_exp_f32_e32 v145, v145
	v_mul_f32_e32 v152, 0xbfb8aa3b, v159
	v_exp_f32_e32 v152, v152
	v_rcp_f32_e32 v158, v140
	v_add_f32_e32 v140, 1.0, v145
	v_mul_f32_e32 v145, 0xbfb8aa3b, v160
	v_rcp_f32_e32 v163, v140
	v_add_f32_e32 v140, 1.0, v152
	v_exp_f32_e32 v152, v145
	v_mul_f32_e32 v145, 0xbfb8aa3b, v161
	v_exp_f32_e32 v159, v145
	v_rcp_f32_e32 v145, v140
	v_add_f32_e32 v140, 1.0, v152
	v_rcp_f32_e32 v171, v140
	v_add_f32_e32 v140, 1.0, v159
	v_pk_fma_f32 v[144:145], v[144:145], s[30:31], 0.5 op_sel_hi:[1,0,0]
	v_rcp_f32_e32 v159, v140
	v_pk_fma_f32 v[160:161], v[162:163], s[30:31], 0.5 op_sel_hi:[1,0,0]
	v_cvt_u32_f32_e32 v140, v145
	v_cvt_u32_f32_e32 v144, v144
	v_cvt_u32_f32_e32 v145, v161
	v_cvt_u32_f32_e32 v152, v160
	v_lshlrev_b32_e32 v140, 8, v140
	v_lshlrev_b32_e32 v144, 8, v144
	v_or_b32_e32 v140, v140, v145
	v_or_b32_e32 v152, v144, v152
	v_pk_fma_f32 v[144:145], v[170:171], s[30:31], 0.5 op_sel_hi:[1,0,0]
	s_nop 0
	v_cvt_u32_f32_sdwa v160, v144 dst_sel:WORD_1 dst_unused:UNUSED_PAD src0_sel:DWORD
	v_cvt_u32_f32_sdwa v161, v145 dst_sel:WORD_1 dst_unused:UNUSED_PAD src0_sel:DWORD
	v_pk_fma_f32 v[144:145], v[158:159], s[30:31], 0.5 op_sel_hi:[1,0,0]
	v_or_b32_e32 v152, v152, v160
	v_cvt_u32_f32_sdwa v145, v145 dst_sel:BYTE_3 dst_unused:UNUSED_PAD src0_sel:DWORD
	v_cvt_u32_f32_sdwa v144, v144 dst_sel:BYTE_3 dst_unused:UNUSED_PAD src0_sel:DWORD
	v_or_b32_e32 v140, v140, v161
	v_or_b32_e32 v145, v140, v145
	v_or_b32_e32 v144, v152, v144
	v_add_u32_e32 v140, 32, v143
	global_store_dwordx2 v140, v[144:145], s[22:23]
	s_cbranch_vccnz .LBB0_447
	v_add_u32_e32 v144, 48, v80
	v_mov_b32_e32 v145, v81
	v_lshl_add_u64 v[144:145], v[144:145], 2, s[14:15]
	global_load_dword v250, v[252:253], off offset:512
	s_waitcnt vmcnt(3)
	v_mov_b32_e32 v138, v251
	v_fmamk_f32 v138, v138, 0x3a800000, v147
	v_rsq_f32_e32 v138, v138
; __device__ __forceinline__ unsigned gq8(float x) { return (unsigned)(sigmoidf_(x) * 255.0f + 0.5f); }
;     __device__ __forceinline__ void operator()(const f32x4 (&acc)[2][2][4][2], const pg8::Unit& u, int wr, int wc, int fr_, int fq_) const {
;     ...
; #pragma unroll
;             for (int ai = 0; ai < 2; ++ai)
; #pragma unroll
;                 for (int m = 0; m < 4; ++m) { const unsigned row = (unsigned)(u.pm * 256 + 128 * ai + 64 * wr + 16 * m + fr);
;                     const float rin = rsq ? __builtin_amdgcn_rsqf(rsq[row] * (1.0f / DM) + 1e-6f) : 1.0f;
; #pragma unroll
;                     for (int bj = 0; bj < 2; ++bj) { const f32x4 a0 = acc[ai][bj][m][0] * rin, a1 = acc[ai][bj][m][1] * rin; u32x2 w;
;                         w.x = gq8(a0[0]) | (gq8(a0[1]) << 8) | (gq8(a0[2]) << 16) | (gq8(a0[3]) << 24);
;                         w.y = gq8(a1[0]) | (gq8(a1[1]) << 8) | (gq8(a1[2]) << 16) | (gq8(a1[3]) << 24);
;                         *(u32x2*)((unsigned char*)brg + (row * 3072u + (unsigned)((t - 12) * 256 + 64 * wc + 32 * bj + 8 * fq))) = w; } }
.LBB0_447:
	s_nop 0
	v_pk_mul_f32 v[158:159], v[76:77], v[138:139] op_sel_hi:[1,0]
	v_pk_mul_f32 v[144:145], v[78:79], v[138:139] op_sel_hi:[1,0]
	v_mul_f32_e32 v143, 0xbfb8aa3b, v158
	v_exp_f32_e32 v143, v143
	v_mul_f32_e32 v152, 0xbfb8aa3b, v159
	v_exp_f32_e32 v152, v152
	v_mul_f32_e32 v144, 0xbfb8aa3b, v144
	v_add_f32_e32 v143, 1.0, v143
	v_rcp_f32_e32 v162, v143
	v_add_f32_e32 v143, 1.0, v152
	v_exp_f32_e32 v152, v144
	v_mul_f32_e32 v144, 0xbfb8aa3b, v145
	v_exp_f32_e32 v145, v144
	v_pk_mul_f32 v[158:159], v[72:73], v[138:139] op_sel_hi:[1,0]
	v_rcp_f32_e32 v144, v143
	v_add_f32_e32 v143, 1.0, v152
	v_rcp_f32_e32 v170, v143
	v_add_f32_e32 v143, 1.0, v145
	v_mul_f32_e32 v145, 0xbfb8aa3b, v158
	v_exp_f32_e32 v145, v145
	v_mul_f32_e32 v152, 0xbfb8aa3b, v159
	v_exp_f32_e32 v152, v152
	v_pk_mul_f32 v[160:161], v[74:75], v[138:139] op_sel_hi:[1,0]
	v_rcp_f32_e32 v158, v143
	v_add_f32_e32 v143, 1.0, v145
	v_mul_f32_e32 v145, 0xbfb8aa3b, v160
	v_rcp_f32_e32 v163, v143
	v_add_f32_e32 v143, 1.0, v152
	v_exp_f32_e32 v152, v145
	v_mul_f32_e32 v145, 0xbfb8aa3b, v161
	v_exp_f32_e32 v159, v145
	v_rcp_f32_e32 v145, v143
	v_add_f32_e32 v143, 1.0, v152
	v_rcp_f32_e32 v171, v143
	v_add_f32_e32 v143, 1.0, v159
	v_pk_fma_f32 v[144:145], v[144:145], s[30:31], 0.5 op_sel_hi:[1,0,0]
	v_rcp_f32_e32 v159, v143
	v_pk_fma_f32 v[160:161], v[162:163], s[30:31], 0.5 op_sel_hi:[1,0,0]
	v_cvt_u32_f32_e32 v143, v145
	v_cvt_u32_f32_e32 v144, v144
	v_cvt_u32_f32_e32 v145, v161
	v_cvt_u32_f32_e32 v152, v160
	v_lshlrev_b32_e32 v143, 8, v143
	v_lshlrev_b32_e32 v144, 8, v144
	v_or_b32_e32 v143, v143, v145
	v_or_b32_e32 v152, v144, v152
	v_pk_fma_f32 v[144:145], v[170:171], s[30:31], 0.5 op_sel_hi:[1,0,0]
	v_add_u32_e32 v141, 0xc000, v141
	v_cvt_u32_f32_sdwa v160, v144 dst_sel:WORD_1 dst_unused:UNUSED_PAD src0_sel:DWORD
	v_cvt_u32_f32_sdwa v161, v145 dst_sel:WORD_1 dst_unused:UNUSED_PAD src0_sel:DWORD
	v_pk_fma_f32 v[144:145], v[158:159], s[30:31], 0.5 op_sel_hi:[1,0,0]
	v_pk_mul_f32 v[158:159], v[68:69], v[138:139] op_sel_hi:[1,0]
	v_cvt_u32_f32_sdwa v145, v145 dst_sel:BYTE_3 dst_unused:UNUSED_PAD src0_sel:DWORD
	v_cvt_u32_f32_sdwa v144, v144 dst_sel:BYTE_3 dst_unused:UNUSED_PAD src0_sel:DWORD
	v_or_b32_e32 v143, v143, v161
	v_or_b32_e32 v152, v152, v160
	v_or_b32_e32 v145, v143, v145
	v_mul_f32_e32 v143, 0xbfb8aa3b, v158
	v_exp_f32_e32 v143, v143
	v_add_u32_e32 v140, v141, v139
	v_or_b32_e32 v144, v152, v144
	global_store_dwordx2 v140, v[144:145], s[22:23]
	v_pk_mul_f32 v[144:145], v[70:71], v[138:139] op_sel_hi:[1,0]
	v_mul_f32_e32 v152, 0xbfb8aa3b, v159
	v_pk_mul_f32 v[160:161], v[66:67], v[138:139] op_sel_hi:[1,0]
	v_exp_f32_e32 v152, v152
	v_pk_mul_f32 v[158:159], v[64:65], v[138:139] op_sel_hi:[1,0]
	v_add_f32_e32 v138, 1.0, v143
	v_mul_f32_e32 v143, 0xbfb8aa3b, v144
	v_exp_f32_e32 v143, v143
	v_mul_f32_e32 v144, 0xbfb8aa3b, v145
	v_exp_f32_e32 v145, v144
	v_rcp_f32_e32 v162, v138
	v_add_f32_e32 v138, 1.0, v152
	v_rcp_f32_e32 v144, v138
	v_add_f32_e32 v138, 1.0, v143
	v_mul_f32_e32 v143, 0xbfb8aa3b, v158
	v_rcp_f32_e32 v170, v138
	v_add_f32_e32 v138, 1.0, v145
	v_exp_f32_e32 v143, v143
	v_mul_f32_e32 v145, 0xbfb8aa3b, v159
	v_exp_f32_e32 v145, v145
	v_rcp_f32_e32 v158, v138
	v_add_f32_e32 v138, 1.0, v143
	v_mul_f32_e32 v143, 0xbfb8aa3b, v160
	v_rcp_f32_e32 v163, v138
	v_add_f32_e32 v138, 1.0, v145
	v_exp_f32_e32 v143, v143
	v_mul_f32_e32 v145, 0xbfb8aa3b, v161
	v_exp_f32_e32 v152, v145
	v_rcp_f32_e32 v145, v138
	v_add_f32_e32 v138, 1.0, v143
	v_rcp_f32_e32 v171, v138
	v_add_f32_e32 v138, 1.0, v152
	v_pk_fma_f32 v[144:145], v[144:145], s[30:31], 0.5 op_sel_hi:[1,0,0]
	v_rcp_f32_e32 v159, v138
	v_pk_fma_f32 v[160:161], v[162:163], s[30:31], 0.5 op_sel_hi:[1,0,0]
	v_cvt_u32_f32_e32 v138, v145
	v_cvt_u32_f32_e32 v143, v144
	v_cvt_u32_f32_e32 v144, v161
	v_cvt_u32_f32_e32 v145, v160
	v_lshlrev_b32_e32 v138, 8, v138
	v_lshlrev_b32_e32 v143, 8, v143
	v_or_b32_e32 v138, v138, v144
	v_or_b32_e32 v143, v143, v145
	v_pk_fma_f32 v[144:145], v[170:171], s[30:31], 0.5 op_sel_hi:[1,0,0]
	s_and_b64 vcc, exec, s[6:7]
	v_cvt_u32_f32_sdwa v152, v144 dst_sel:WORD_1 dst_unused:UNUSED_PAD src0_sel:DWORD
	v_cvt_u32_f32_sdwa v160, v145 dst_sel:WORD_1 dst_unused:UNUSED_PAD src0_sel:DWORD
	v_pk_fma_f32 v[144:145], v[158:159], s[30:31], 0.5 op_sel_hi:[1,0,0]
	v_or_b32_e32 v143, v143, v152
	v_cvt_u32_f32_sdwa v145, v145 dst_sel:BYTE_3 dst_unused:UNUSED_PAD src0_sel:DWORD
	v_cvt_u32_f32_sdwa v144, v144 dst_sel:BYTE_3 dst_unused:UNUSED_PAD src0_sel:DWORD
	v_or_b32_e32 v138, v138, v160
	v_or_b32_e32 v145, v138, v145
	v_or_b32_e32 v144, v143, v144
	v_add_u32_e32 v138, 32, v140
	global_store_dwordx2 v138, v[144:145], s[22:23]
	v_mov_b32_e32 v138, 1.0
	v_mov_b32_e32 v140, 1.0
	s_cbranch_vccnz .LBB0_449
	v_add_u32_e32 v144, 0x80, v80
	v_mov_b32_e32 v145, v81
	v_lshl_add_u64 v[144:145], v[144:145], 2, s[14:15]
	global_load_dword v251, v[252:253], off offset:576
	s_waitcnt vmcnt(3)
	v_mov_b32_e32 v140, v250
	v_fmamk_f32 v140, v140, 0x3a800000, v147
	v_rsq_f32_e32 v140, v140
; __device__ __forceinline__ unsigned gq8(float x) { return (unsigned)(sigmoidf_(x) * 255.0f + 0.5f); }
;     __device__ __forceinline__ void operator()(const f32x4 (&acc)[2][2][4][2], const pg8::Unit& u, int wr, int wc, int fr_, int fq_) const {
;     ...
; #pragma unroll
;             for (int ai = 0; ai < 2; ++ai)
; #pragma unroll
;                 for (int m = 0; m < 4; ++m) { const unsigned row = (unsigned)(u.pm * 256 + 128 * ai + 64 * wr + 16 * m + fr);
;                     const float rin = rsq ? __builtin_amdgcn_rsqf(rsq[row] * (1.0f / DM) + 1e-6f) : 1.0f;
; #pragma unroll
;                     for (int bj = 0; bj < 2; ++bj) { const f32x4 a0 = acc[ai][bj][m][0] * rin, a1 = acc[ai][bj][m][1] * rin; u32x2 w;
;                         w.x = gq8(a0[0]) | (gq8(a0[1]) << 8) | (gq8(a0[2]) << 16) | (gq8(a0[3]) << 24);
;                         w.y = gq8(a1[0]) | (gq8(a1[1]) << 8) | (gq8(a1[2]) << 16) | (gq8(a1[3]) << 24);
;                         *(u32x2*)((unsigned char*)brg + (row * 3072u + (unsigned)((t - 12) * 256 + 64 * wc + 32 * bj + 8 * fq))) = w; } }
.LBB0_449:
	v_add_u32_e32 v141, 0x3c000, v141
	v_pk_mul_f32 v[158:159], v[60:61], v[140:141] op_sel_hi:[1,0]
	v_pk_mul_f32 v[144:145], v[62:63], v[140:141] op_sel_hi:[1,0]
	v_mul_f32_e32 v152, 0xbfb8aa3b, v158
	v_exp_f32_e32 v152, v152
	v_mul_f32_e32 v158, 0xbfb8aa3b, v159
	v_exp_f32_e32 v163, v158
	v_mul_f32_e32 v144, 0xbfb8aa3b, v144
	v_add_f32_e32 v152, 1.0, v152
	v_rcp_f32_e32 v162, v152
	v_add_f32_e32 v152, 1.0, v163
	v_exp_f32_e32 v163, v144
	v_mul_f32_e32 v144, 0xbfb8aa3b, v145
	v_pk_mul_f32 v[158:159], v[56:57], v[140:141] op_sel_hi:[1,0]
	v_exp_f32_e32 v145, v144
	v_rcp_f32_e32 v144, v152
	v_add_f32_e32 v152, 1.0, v163
	v_rcp_f32_e32 v170, v152
	v_mul_f32_e32 v152, 0xbfb8aa3b, v158
	v_exp_f32_e32 v152, v152
	v_mul_f32_e32 v158, 0xbfb8aa3b, v159
	v_exp_f32_e32 v159, v158
	v_add_f32_e32 v145, 1.0, v145
	v_pk_mul_f32 v[160:161], v[58:59], v[140:141] op_sel_hi:[1,0]
	v_rcp_f32_e32 v158, v145
	v_add_f32_e32 v145, 1.0, v152
	v_rcp_f32_e32 v163, v145
	v_add_f32_e32 v145, 1.0, v159
	v_mul_f32_e32 v152, 0xbfb8aa3b, v160
	v_exp_f32_e32 v152, v152
	v_mul_f32_e32 v159, 0xbfb8aa3b, v161
	v_rcp_f32_e32 v145, v145
	v_exp_f32_e32 v159, v159
	v_add_f32_e32 v152, 1.0, v152
	v_rcp_f32_e32 v171, v152
	v_pk_fma_f32 v[144:145], v[144:145], s[30:31], 0.5 op_sel_hi:[1,0,0]
	v_add_f32_e32 v152, 1.0, v159
	v_pk_fma_f32 v[160:161], v[162:163], s[30:31], 0.5 op_sel_hi:[1,0,0]
	v_cvt_u32_f32_e32 v145, v145
	v_cvt_u32_f32_e32 v144, v144
	v_rcp_f32_e32 v159, v152
	v_cvt_u32_f32_e32 v152, v161
	v_cvt_u32_f32_e32 v160, v160
	v_lshlrev_b32_e32 v145, 8, v145
	v_lshlrev_b32_e32 v144, 8, v144
	v_or_b32_e32 v152, v145, v152
	v_or_b32_e32 v160, v144, v160
	v_pk_fma_f32 v[144:145], v[170:171], s[30:31], 0.5 op_sel_hi:[1,0,0]
	v_add_u32_e32 v143, v141, v139
	v_cvt_u32_f32_sdwa v161, v144 dst_sel:WORD_1 dst_unused:UNUSED_PAD src0_sel:DWORD
	v_cvt_u32_f32_sdwa v162, v145 dst_sel:WORD_1 dst_unused:UNUSED_PAD src0_sel:DWORD
	v_pk_fma_f32 v[144:145], v[158:159], s[30:31], 0.5 op_sel_hi:[1,0,0]
	s_and_b64 vcc, exec, s[6:7]
	v_cvt_u32_f32_sdwa v144, v144 dst_sel:BYTE_3 dst_unused:UNUSED_PAD src0_sel:DWORD
	v_cvt_u32_f32_sdwa v145, v145 dst_sel:BYTE_3 dst_unused:UNUSED_PAD src0_sel:DWORD
	v_or_b32_e32 v158, v160, v161
	v_or_b32_e32 v152, v152, v162
	v_or_b32_e32 v144, v158, v144
	v_pk_mul_f32 v[158:159], v[52:53], v[140:141] op_sel_hi:[1,0]
	v_or_b32_e32 v145, v152, v145
	v_mul_f32_e32 v152, 0xbfb8aa3b, v158
	v_exp_f32_e32 v152, v152
	global_store_dwordx2 v143, v[144:145], s[22:23]
	v_pk_mul_f32 v[144:145], v[54:55], v[140:141] op_sel_hi:[1,0]
	v_mul_f32_e32 v158, 0xbfb8aa3b, v159
	v_exp_f32_e32 v163, v158
	v_mul_f32_e32 v144, 0xbfb8aa3b, v144
	v_pk_mul_f32 v[160:161], v[50:51], v[140:141] op_sel_hi:[1,0]
	v_pk_mul_f32 v[158:159], v[48:49], v[140:141] op_sel_hi:[1,0]
	v_add_f32_e32 v140, 1.0, v152
	v_exp_f32_e32 v152, v144
	v_mul_f32_e32 v144, 0xbfb8aa3b, v145
	v_exp_f32_e32 v145, v144
	v_rcp_f32_e32 v162, v140
	v_add_f32_e32 v140, 1.0, v163
	v_rcp_f32_e32 v144, v140
	v_add_f32_e32 v140, 1.0, v152
	v_rcp_f32_e32 v170, v140
	v_add_f32_e32 v140, 1.0, v145
	v_mul_f32_e32 v145, 0xbfb8aa3b, v158
	v_exp_f32_e32 v145, v145
	v_mul_f32_e32 v152, 0xbfb8aa3b, v159
	v_exp_f32_e32 v152, v152
	v_rcp_f32_e32 v158, v140
	v_add_f32_e32 v140, 1.0, v145
	v_mul_f32_e32 v145, 0xbfb8aa3b, v160
	v_rcp_f32_e32 v163, v140
	v_add_f32_e32 v140, 1.0, v152
	v_exp_f32_e32 v152, v145
	v_mul_f32_e32 v145, 0xbfb8aa3b, v161
	v_exp_f32_e32 v159, v145
	v_rcp_f32_e32 v145, v140
	v_add_f32_e32 v140, 1.0, v152
	v_rcp_f32_e32 v171, v140
	v_add_f32_e32 v140, 1.0, v159
	v_pk_fma_f32 v[144:145], v[144:145], s[30:31], 0.5 op_sel_hi:[1,0,0]
	v_rcp_f32_e32 v159, v140
	v_pk_fma_f32 v[160:161], v[162:163], s[30:31], 0.5 op_sel_hi:[1,0,0]
	v_cvt_u32_f32_e32 v140, v145
	v_cvt_u32_f32_e32 v144, v144
	v_cvt_u32_f32_e32 v145, v161
	v_cvt_u32_f32_e32 v152, v160
	v_lshlrev_b32_e32 v140, 8, v140
	v_lshlrev_b32_e32 v144, 8, v144
	v_or_b32_e32 v140, v140, v145
	v_or_b32_e32 v152, v144, v152
	v_pk_fma_f32 v[144:145], v[170:171], s[30:31], 0.5 op_sel_hi:[1,0,0]
	s_nop 0
	v_cvt_u32_f32_sdwa v160, v144 dst_sel:WORD_1 dst_unused:UNUSED_PAD src0_sel:DWORD
	v_cvt_u32_f32_sdwa v161, v145 dst_sel:WORD_1 dst_unused:UNUSED_PAD src0_sel:DWORD
	v_pk_fma_f32 v[144:145], v[158:159], s[30:31], 0.5 op_sel_hi:[1,0,0]
	v_or_b32_e32 v152, v152, v160
	v_cvt_u32_f32_sdwa v145, v145 dst_sel:BYTE_3 dst_unused:UNUSED_PAD src0_sel:DWORD
	v_cvt_u32_f32_sdwa v144, v144 dst_sel:BYTE_3 dst_unused:UNUSED_PAD src0_sel:DWORD
	v_or_b32_e32 v140, v140, v161
	v_or_b32_e32 v145, v140, v145
	v_or_b32_e32 v144, v152, v144
	v_add_u32_e32 v140, 32, v143
	global_store_dwordx2 v140, v[144:145], s[22:23]
	s_cbranch_vccnz .LBB0_451
	v_add_u32_e32 v144, 0x90, v80
	v_mov_b32_e32 v145, v81
	v_lshl_add_u64 v[144:145], v[144:145], 2, s[14:15]
	global_load_dword v250, v[252:253], off offset:640
	s_waitcnt vmcnt(3)
	v_mov_b32_e32 v138, v251
	v_fmamk_f32 v138, v138, 0x3a800000, v147
	v_rsq_f32_e32 v138, v138
; __device__ __forceinline__ float sigmoidf_(float x) { return __builtin_amdgcn_rcpf(1.0f + __expf(-x)); }
; __device__ __forceinline__ unsigned gq8(float x) { return (unsigned)(sigmoidf_(x) * 255.0f + 0.5f); }
;     __device__ __forceinline__ void operator()(const f32x4 (&acc)[2][2][4][2], const pg8::Unit& u, int wr, int wc, int fr_, int fq_) const {
;     ...
;             for (int ai = 0; ai < 2; ++ai)
; #pragma unroll
;                 for (int m = 0; m < 4; ++m) { const unsigned row = (unsigned)(u.pm * 256 + 128 * ai + 64 * wr + 16 * m + fr);
;                     const float rin = rsq ? __builtin_amdgcn_rsqf(rsq[row] * (1.0f / DM) + 1e-6f) : 1.0f;
; #pragma unroll
;                     for (int bj = 0; bj < 2; ++bj) { const f32x4 a0 = acc[ai][bj][m][0] * rin, a1 = acc[ai][bj][m][1] * rin; u32x2 w;
;                         w.x = gq8(a0[0]) | (gq8(a0[1]) << 8) | (gq8(a0[2]) << 16) | (gq8(a0[3]) << 24);
;                         w.y = gq8(a1[0]) | (gq8(a1[1]) << 8) | (gq8(a1[2]) << 16) | (gq8(a1[3]) << 24);
;                         *(u32x2*)((unsigned char*)brg + (row * 3072u + (unsigned)((t - 12) * 256 + 64 * wc + 32 * bj + 8 * fq))) = w; } }
.LBB0_451:
	s_nop 0
	v_pk_mul_f32 v[158:159], v[44:45], v[138:139] op_sel_hi:[1,0]
	v_pk_mul_f32 v[144:145], v[46:47], v[138:139] op_sel_hi:[1,0]
	v_mul_f32_e32 v143, 0xbfb8aa3b, v158
	v_exp_f32_e32 v143, v143
	v_mul_f32_e32 v152, 0xbfb8aa3b, v159
	v_exp_f32_e32 v152, v152
	v_mul_f32_e32 v144, 0xbfb8aa3b, v144
	v_add_f32_e32 v143, 1.0, v143
	v_rcp_f32_e32 v162, v143
	v_add_f32_e32 v143, 1.0, v152
	v_exp_f32_e32 v152, v144
	v_mul_f32_e32 v144, 0xbfb8aa3b, v145
	v_exp_f32_e32 v145, v144
	v_pk_mul_f32 v[158:159], v[40:41], v[138:139] op_sel_hi:[1,0]
	v_rcp_f32_e32 v144, v143
	v_add_f32_e32 v143, 1.0, v152
	v_rcp_f32_e32 v170, v143
	v_add_f32_e32 v143, 1.0, v145
	v_mul_f32_e32 v145, 0xbfb8aa3b, v158
	v_exp_f32_e32 v145, v145
	v_mul_f32_e32 v152, 0xbfb8aa3b, v159
	v_exp_f32_e32 v152, v152
	v_pk_mul_f32 v[160:161], v[42:43], v[138:139] op_sel_hi:[1,0]
	v_rcp_f32_e32 v158, v143
	v_add_f32_e32 v143, 1.0, v145
	v_mul_f32_e32 v145, 0xbfb8aa3b, v160
	v_rcp_f32_e32 v163, v143
	v_add_f32_e32 v143, 1.0, v152
	v_exp_f32_e32 v152, v145
	v_mul_f32_e32 v145, 0xbfb8aa3b, v161
	v_exp_f32_e32 v159, v145
	v_rcp_f32_e32 v145, v143
	v_add_f32_e32 v143, 1.0, v152
	v_rcp_f32_e32 v171, v143
	v_add_f32_e32 v143, 1.0, v159
	v_pk_fma_f32 v[144:145], v[144:145], s[30:31], 0.5 op_sel_hi:[1,0,0]
	v_rcp_f32_e32 v159, v143
	v_pk_fma_f32 v[160:161], v[162:163], s[30:31], 0.5 op_sel_hi:[1,0,0]
	v_cvt_u32_f32_e32 v143, v145
	v_cvt_u32_f32_e32 v144, v144
	v_cvt_u32_f32_e32 v145, v161
	v_cvt_u32_f32_e32 v152, v160
	v_lshlrev_b32_e32 v143, 8, v143
	v_lshlrev_b32_e32 v144, 8, v144
	v_or_b32_e32 v143, v143, v145
	v_or_b32_e32 v152, v144, v152
	v_pk_fma_f32 v[144:145], v[170:171], s[30:31], 0.5 op_sel_hi:[1,0,0]
	v_add_u32_e32 v141, 0xc000, v141
	v_cvt_u32_f32_sdwa v160, v144 dst_sel:WORD_1 dst_unused:UNUSED_PAD src0_sel:DWORD
	v_cvt_u32_f32_sdwa v161, v145 dst_sel:WORD_1 dst_unused:UNUSED_PAD src0_sel:DWORD
	v_pk_fma_f32 v[144:145], v[158:159], s[30:31], 0.5 op_sel_hi:[1,0,0]
	v_pk_mul_f32 v[158:159], v[36:37], v[138:139] op_sel_hi:[1,0]
	v_cvt_u32_f32_sdwa v145, v145 dst_sel:BYTE_3 dst_unused:UNUSED_PAD src0_sel:DWORD
	v_cvt_u32_f32_sdwa v144, v144 dst_sel:BYTE_3 dst_unused:UNUSED_PAD src0_sel:DWORD
	v_or_b32_e32 v143, v143, v161
	v_or_b32_e32 v152, v152, v160
	v_or_b32_e32 v145, v143, v145
	v_mul_f32_e32 v143, 0xbfb8aa3b, v158
	v_exp_f32_e32 v143, v143
	v_add_u32_e32 v140, v141, v139
	v_or_b32_e32 v144, v152, v144
	global_store_dwordx2 v140, v[144:145], s[22:23]
	v_pk_mul_f32 v[144:145], v[38:39], v[138:139] op_sel_hi:[1,0]
	v_mul_f32_e32 v152, 0xbfb8aa3b, v159
	v_pk_mul_f32 v[160:161], v[34:35], v[138:139] op_sel_hi:[1,0]
	v_exp_f32_e32 v152, v152
	v_pk_mul_f32 v[158:159], v[32:33], v[138:139] op_sel_hi:[1,0]
	v_add_f32_e32 v138, 1.0, v143
	v_mul_f32_e32 v143, 0xbfb8aa3b, v144
	v_exp_f32_e32 v143, v143
	v_mul_f32_e32 v144, 0xbfb8aa3b, v145
	v_exp_f32_e32 v145, v144
	v_rcp_f32_e32 v162, v138
	v_add_f32_e32 v138, 1.0, v152
	v_rcp_f32_e32 v144, v138
	v_add_f32_e32 v138, 1.0, v143
	v_mul_f32_e32 v143, 0xbfb8aa3b, v158
	v_rcp_f32_e32 v170, v138
	v_add_f32_e32 v138, 1.0, v145
	v_exp_f32_e32 v143, v143
	v_mul_f32_e32 v145, 0xbfb8aa3b, v159
	v_exp_f32_e32 v145, v145
	v_rcp_f32_e32 v158, v138
	v_add_f32_e32 v138, 1.0, v143
	v_mul_f32_e32 v143, 0xbfb8aa3b, v160
	v_rcp_f32_e32 v163, v138
	v_add_f32_e32 v138, 1.0, v145
	v_exp_f32_e32 v143, v143
	v_mul_f32_e32 v145, 0xbfb8aa3b, v161
	v_exp_f32_e32 v152, v145
	v_rcp_f32_e32 v145, v138
	v_add_f32_e32 v138, 1.0, v143
	v_rcp_f32_e32 v171, v138
	v_add_f32_e32 v138, 1.0, v152
	v_pk_fma_f32 v[144:145], v[144:145], s[30:31], 0.5 op_sel_hi:[1,0,0]
	v_rcp_f32_e32 v159, v138
	v_pk_fma_f32 v[160:161], v[162:163], s[30:31], 0.5 op_sel_hi:[1,0,0]
	v_cvt_u32_f32_e32 v138, v145
	v_cvt_u32_f32_e32 v143, v144
	v_cvt_u32_f32_e32 v144, v161
	v_cvt_u32_f32_e32 v145, v160
	v_lshlrev_b32_e32 v138, 8, v138
	v_lshlrev_b32_e32 v143, 8, v143
	v_or_b32_e32 v138, v138, v144
	v_or_b32_e32 v143, v143, v145
	v_pk_fma_f32 v[144:145], v[170:171], s[30:31], 0.5 op_sel_hi:[1,0,0]
	s_and_b64 vcc, exec, s[6:7]
	v_cvt_u32_f32_sdwa v152, v144 dst_sel:WORD_1 dst_unused:UNUSED_PAD src0_sel:DWORD
	v_cvt_u32_f32_sdwa v160, v145 dst_sel:WORD_1 dst_unused:UNUSED_PAD src0_sel:DWORD
	v_pk_fma_f32 v[144:145], v[158:159], s[30:31], 0.5 op_sel_hi:[1,0,0]
	v_or_b32_e32 v143, v143, v152
	v_cvt_u32_f32_sdwa v145, v145 dst_sel:BYTE_3 dst_unused:UNUSED_PAD src0_sel:DWORD
	v_cvt_u32_f32_sdwa v144, v144 dst_sel:BYTE_3 dst_unused:UNUSED_PAD src0_sel:DWORD
	v_or_b32_e32 v138, v138, v160
	v_or_b32_e32 v145, v138, v145
	v_or_b32_e32 v144, v143, v144
	v_add_u32_e32 v138, 32, v140
	global_store_dwordx2 v138, v[144:145], s[22:23]
	v_mov_b32_e32 v138, 1.0
	v_mov_b32_e32 v140, 1.0
	s_cbranch_vccnz .LBB0_453
	v_add_u32_e32 v144, 0xa0, v80
	v_mov_b32_e32 v145, v81
	v_lshl_add_u64 v[144:145], v[144:145], 2, s[14:15]
	global_load_dword v251, v[252:253], off offset:704
	s_waitcnt vmcnt(3)
	v_mov_b32_e32 v140, v250
	v_fmamk_f32 v140, v140, 0x3a800000, v147
	v_rsq_f32_e32 v140, v140
; __device__ __forceinline__ float sigmoidf_(float x) { return __builtin_amdgcn_rcpf(1.0f + __expf(-x)); }
; __device__ __forceinline__ unsigned gq8(float x) { return (unsigned)(sigmoidf_(x) * 255.0f + 0.5f); }
;     __device__ __forceinline__ void operator()(const f32x4 (&acc)[2][2][4][2], const pg8::Unit& u, int wr, int wc, int fr_, int fq_) const {
;     ...
;             for (int ai = 0; ai < 2; ++ai)
; #pragma unroll
;                 for (int m = 0; m < 4; ++m) { const unsigned row = (unsigned)(u.pm * 256 + 128 * ai + 64 * wr + 16 * m + fr);
;                     const float rin = rsq ? __builtin_amdgcn_rsqf(rsq[row] * (1.0f / DM) + 1e-6f) : 1.0f;
; #pragma unroll
;                     for (int bj = 0; bj < 2; ++bj) { const f32x4 a0 = acc[ai][bj][m][0] * rin, a1 = acc[ai][bj][m][1] * rin; u32x2 w;
;                         w.x = gq8(a0[0]) | (gq8(a0[1]) << 8) | (gq8(a0[2]) << 16) | (gq8(a0[3]) << 24);
;                         w.y = gq8(a1[0]) | (gq8(a1[1]) << 8) | (gq8(a1[2]) << 16) | (gq8(a1[3]) << 24);
;                         *(u32x2*)((unsigned char*)brg + (row * 3072u + (unsigned)((t - 12) * 256 + 64 * wc + 32 * bj + 8 * fq))) = w; } }
.LBB0_453:
	v_add_u32_e32 v141, 0xc000, v141
	v_pk_mul_f32 v[158:159], v[28:29], v[140:141] op_sel_hi:[1,0]
	v_add_u32_e32 v139, v141, v139
	v_pk_mul_f32 v[144:145], v[30:31], v[140:141] op_sel_hi:[1,0]
	v_pk_mul_f32 v[160:161], v[26:27], v[140:141] op_sel_hi:[1,0]
	v_mul_f32_e32 v141, 0xbfb8aa3b, v158
	v_exp_f32_e32 v141, v141
	v_mul_f32_e32 v143, 0xbfb8aa3b, v159
	v_exp_f32_e32 v143, v143
	s_and_b64 vcc, exec, s[6:7]
	v_pk_mul_f32 v[158:159], v[24:25], v[140:141] op_sel_hi:[1,0]
	v_add_f32_e32 v141, 1.0, v141
	v_rcp_f32_e32 v162, v141
	v_add_f32_e32 v141, 1.0, v143
	v_mul_f32_e32 v143, 0xbfb8aa3b, v144
	v_exp_f32_e32 v143, v143
	v_mul_f32_e32 v144, 0xbfb8aa3b, v145
	v_exp_f32_e32 v145, v144
	v_rcp_f32_e32 v144, v141
	v_add_f32_e32 v141, 1.0, v143
	v_mul_f32_e32 v143, 0xbfb8aa3b, v158
	v_rcp_f32_e32 v170, v141
	v_add_f32_e32 v141, 1.0, v145
	v_exp_f32_e32 v143, v143
	v_mul_f32_e32 v145, 0xbfb8aa3b, v159
	v_exp_f32_e32 v145, v145
	v_rcp_f32_e32 v158, v141
	v_add_f32_e32 v141, 1.0, v143
	v_mul_f32_e32 v143, 0xbfb8aa3b, v160
	v_rcp_f32_e32 v163, v141
	v_add_f32_e32 v141, 1.0, v145
	v_exp_f32_e32 v143, v143
	v_mul_f32_e32 v145, 0xbfb8aa3b, v161
	v_exp_f32_e32 v152, v145
	v_rcp_f32_e32 v145, v141
	v_add_f32_e32 v141, 1.0, v143
	v_rcp_f32_e32 v171, v141
	v_add_f32_e32 v141, 1.0, v152
	v_pk_fma_f32 v[144:145], v[144:145], s[30:31], 0.5 op_sel_hi:[1,0,0]
	v_rcp_f32_e32 v159, v141
	v_pk_fma_f32 v[160:161], v[162:163], s[30:31], 0.5 op_sel_hi:[1,0,0]
	v_cvt_u32_f32_e32 v141, v145
	v_cvt_u32_f32_e32 v143, v144
	v_cvt_u32_f32_e32 v144, v161
	v_cvt_u32_f32_e32 v145, v160
	v_lshlrev_b32_e32 v141, 8, v141
	v_lshlrev_b32_e32 v143, 8, v143
	v_or_b32_e32 v141, v141, v144
	v_or_b32_e32 v143, v143, v145
	v_pk_fma_f32 v[144:145], v[170:171], s[30:31], 0.5 op_sel_hi:[1,0,0]
	s_nop 0
	v_cvt_u32_f32_sdwa v152, v144 dst_sel:WORD_1 dst_unused:UNUSED_PAD src0_sel:DWORD
	v_cvt_u32_f32_sdwa v160, v145 dst_sel:WORD_1 dst_unused:UNUSED_PAD src0_sel:DWORD
	v_pk_fma_f32 v[144:145], v[158:159], s[30:31], 0.5 op_sel_hi:[1,0,0]
	v_or_b32_e32 v143, v143, v152
	v_cvt_u32_f32_sdwa v145, v145 dst_sel:BYTE_3 dst_unused:UNUSED_PAD src0_sel:DWORD
	v_cvt_u32_f32_sdwa v144, v144 dst_sel:BYTE_3 dst_unused:UNUSED_PAD src0_sel:DWORD
	v_or_b32_e32 v141, v141, v160
	v_pk_mul_f32 v[158:159], v[20:21], v[140:141] op_sel_hi:[1,0]
	v_or_b32_e32 v145, v141, v145
	v_or_b32_e32 v144, v143, v144
	global_store_dwordx2 v139, v[144:145], s[22:23]
	v_pk_mul_f32 v[144:145], v[22:23], v[140:141] op_sel_hi:[1,0]
	v_pk_mul_f32 v[160:161], v[18:19], v[140:141] op_sel_hi:[1,0]
	v_mul_f32_e32 v141, 0xbfb8aa3b, v158
	v_exp_f32_e32 v143, v141
	v_mul_f32_e32 v141, 0xbfb8aa3b, v159
	v_exp_f32_e32 v152, v141
	v_mul_f32_e32 v144, 0xbfb8aa3b, v144
	v_add_f32_e32 v143, 1.0, v143
	v_rcp_f32_e32 v158, v143
	v_add_f32_e32 v143, 1.0, v152
	v_exp_f32_e32 v152, v144
	v_mul_f32_e32 v144, 0xbfb8aa3b, v145
	v_exp_f32_e32 v145, v144
	v_pk_mul_f32 v[140:141], v[16:17], v[140:141] op_sel_hi:[1,0]
	v_rcp_f32_e32 v144, v143
	v_add_f32_e32 v143, 1.0, v152
	v_mul_f32_e32 v140, 0xbfb8aa3b, v140
	v_rcp_f32_e32 v162, v143
	v_add_f32_e32 v143, 1.0, v145
	v_exp_f32_e32 v145, v140
	v_mul_f32_e32 v140, 0xbfb8aa3b, v141
	v_exp_f32_e32 v141, v140
	v_rcp_f32_e32 v140, v143
	v_add_f32_e32 v143, 1.0, v145
	v_mul_f32_e32 v145, 0xbfb8aa3b, v161
	v_add_f32_e32 v141, 1.0, v141
	v_rcp_f32_e32 v159, v143
	v_mul_f32_e32 v143, 0xbfb8aa3b, v160
	v_exp_f32_e32 v152, v145
	v_rcp_f32_e32 v145, v141
	v_exp_f32_e32 v143, v143
	v_pk_fma_f32 v[158:159], v[158:159], s[30:31], 0.5 op_sel_hi:[1,0,0]
	v_pk_fma_f32 v[144:145], v[144:145], s[30:31], 0.5 op_sel_hi:[1,0,0]
	v_add_f32_e32 v141, 1.0, v143
	v_cvt_u32_f32_e32 v143, v145
	v_cvt_u32_f32_e32 v144, v144
	v_rcp_f32_e32 v163, v141
	v_add_f32_e32 v141, 1.0, v152
	v_cvt_u32_f32_e32 v145, v159
	v_cvt_u32_f32_e32 v152, v158
	v_rcp_f32_e32 v141, v141
	v_lshlrev_b32_e32 v143, 8, v143
	v_lshlrev_b32_e32 v144, 8, v144
	v_or_b32_e32 v143, v143, v145
	v_or_b32_e32 v152, v144, v152
	v_pk_fma_f32 v[144:145], v[162:163], s[30:31], 0.5 op_sel_hi:[1,0,0]
	v_pk_fma_f32 v[140:141], v[140:141], s[30:31], 0.5 op_sel_hi:[1,0,0]
	v_cvt_u32_f32_sdwa v144, v144 dst_sel:WORD_1 dst_unused:UNUSED_PAD src0_sel:DWORD
	v_cvt_u32_f32_sdwa v145, v145 dst_sel:WORD_1 dst_unused:UNUSED_PAD src0_sel:DWORD
	v_cvt_u32_f32_sdwa v141, v141 dst_sel:BYTE_3 dst_unused:UNUSED_PAD src0_sel:DWORD
	v_cvt_u32_f32_sdwa v140, v140 dst_sel:BYTE_3 dst_unused:UNUSED_PAD src0_sel:DWORD
	v_or_b32_e32 v144, v152, v144
	v_or_b32_e32 v143, v143, v145
	v_or_b32_e32 v141, v143, v141
	v_or_b32_e32 v140, v144, v140
	v_add_u32_e32 v143, 32, v139
	global_store_dwordx2 v143, v[140:141], s[22:23]
	s_cbranch_vccnz .LBB0_455
	v_add_u32_e32 v80, 0xb0, v80
	v_lshl_add_u64 v[140:141], v[80:81], 2, s[14:15]
	s_waitcnt vmcnt(2)
	v_mov_b32_e32 v80, v251
	v_fmamk_f32 v80, v80, 0x3a800000, v147
	v_rsq_f32_e32 v138, v80

;     __device__ __forceinline__ void operator()(const f32x4 (&acc)[2][2][4][2], const pg8::Unit& u, int wr, int wc, int fr_, int fq_) const {
;     ...
;                 for (int m = 0; m < 4; ++m) { const int row = u.pm * 256 + 128 * ai + 64 * wr + 16 * m + fr; const int b = row >> 13, s = row & 8191;
;                     const float rin = rsq ? __builtin_amdgcn_rsqf(rsq[row] * (1.0f / DM) + 1e-6f) : 1.0f;
.LBB0_485:
	s_lshl_b32 s6, s38, 8
	s_add_i32 s6, s6, s64
	v_cndmask_b32_e64 v80, 0, 1, s[8:9]
	v_add_u32_e32 v138, s6, v142
	v_cmp_ne_u32_e64 s[6:7], 1, v80
	s_andn2_b64 vcc, exec, s[8:9]
	v_mov_b32_e32 v80, 1.0
	s_cbranch_vccnz .LBB0_487
	v_ashrrev_i32_e32 v139, 31, v138
	v_lshl_add_u64 v[140:141], v[138:139], 2, s[14:15]
	global_load_dword v240, v[140:141], off
	global_load_dword v241, v[140:141], off offset:64
	global_load_dword v242, v[140:141], off offset:128
	global_load_dword v243, v[140:141], off offset:192
	global_load_dword v244, v[140:141], off offset:512
	global_load_dword v245, v[140:141], off offset:576
	global_load_dword v246, v[140:141], off offset:640
	global_load_dword v247, v[140:141], off offset:704
	s_waitcnt vmcnt(0)
	v_mov_b32_e32 v80, v240
	v_fmamk_f32 v80, v80, 0x3a800000, v147
	v_rsq_f32_e32 v80, v80

;     __device__ __forceinline__ void operator()(const f32x4 (&acc)[2][2][4][2], const pg8::Unit& u, int wr, int wc, int fr_, int fq_) const {
;     ...
;                 for (int m = 0; m < 4; ++m) { const int row = u.pm * 256 + 128 * ai + 64 * wr + 16 * m + fr; const int b = row >> 13, s = row & 8191;
;                     const float rin = rsq ? __builtin_amdgcn_rsqf(rsq[row] * (1.0f / DM) + 1e-6f) : 1.0f;
.LBB0_520:
	v_ashrrev_i32_e32 v121, 31, v120
	v_lshl_add_u64 v[122:123], v[120:121], 2, s[14:15]
	v_mov_b32_e32 v80, v241
	v_fmamk_f32 v80, v80, 0x3a800000, v147
	v_rsq_f32_e32 v80, v80
	s_cmp_lt_i32 s36, 9
	s_cbranch_scc0 .LBB0_516

;     __device__ __forceinline__ void operator()(const f32x4 (&acc)[2][2][4][2], const pg8::Unit& u, int wr, int wc, int fr_, int fq_) const {
;     ...
;                 for (int m = 0; m < 4; ++m) { const int row = u.pm * 256 + 128 * ai + 64 * wr + 16 * m + fr; const int b = row >> 13, s = row & 8191;
;                     const float rin = rsq ? __builtin_amdgcn_rsqf(rsq[row] * (1.0f / DM) + 1e-6f) : 1.0f;
.LBB0_550:
	v_ashrrev_i32_e32 v99, 31, v98
	v_lshl_add_u64 v[100:101], v[98:99], 2, s[14:15]
	v_mov_b32_e32 v80, v242
	v_fmamk_f32 v80, v80, 0x3a800000, v147
	v_rsq_f32_e32 v80, v80
	s_cmp_lt_i32 s36, 9
	s_cbranch_scc0 .LBB0_546

;     __device__ __forceinline__ void operator()(const f32x4 (&acc)[2][2][4][2], const pg8::Unit& u, int wr, int wc, int fr_, int fq_) const {
;     ...
;                 for (int m = 0; m < 4; ++m) { const int row = u.pm * 256 + 128 * ai + 64 * wr + 16 * m + fr; const int b = row >> 13, s = row & 8191;
;                     const float rin = rsq ? __builtin_amdgcn_rsqf(rsq[row] * (1.0f / DM) + 1e-6f) : 1.0f;
.LBB0_580:
	v_ashrrev_i32_e32 v83, 31, v82
	v_lshl_add_u64 v[84:85], v[82:83], 2, s[14:15]
	v_mov_b32_e32 v80, v243
	v_fmamk_f32 v80, v80, 0x3a800000, v147
	v_rsq_f32_e32 v80, v80
	s_cmp_lt_i32 s36, 9
	s_cbranch_scc0 .LBB0_576

;     __device__ __forceinline__ void operator()(const f32x4 (&acc)[2][2][4][2], const pg8::Unit& u, int wr, int wc, int fr_, int fq_) const {
;     ...
;                 for (int m = 0; m < 4; ++m) { const int row = u.pm * 256 + 128 * ai + 64 * wr + 16 * m + fr; const int b = row >> 13, s = row & 8191;
;                     const float rin = rsq ? __builtin_amdgcn_rsqf(rsq[row] * (1.0f / DM) + 1e-6f) : 1.0f;
.LBB0_610:
	v_ashrrev_i32_e32 v65, 31, v64
	v_lshl_add_u64 v[66:67], v[64:65], 2, s[14:15]
	v_mov_b32_e32 v65, v244
	v_fmamk_f32 v65, v65, 0x3a800000, v147
	v_rsq_f32_e32 v68, v65
	s_cmp_lt_i32 s36, 9
	s_cbranch_scc0 .LBB0_606

;     __device__ __forceinline__ void operator()(const f32x4 (&acc)[2][2][4][2], const pg8::Unit& u, int wr, int wc, int fr_, int fq_) const {
;     ...
;                 for (int m = 0; m < 4; ++m) { const int row = u.pm * 256 + 128 * ai + 64 * wr + 16 * m + fr; const int b = row >> 13, s = row & 8191;
;                     const float rin = rsq ? __builtin_amdgcn_rsqf(rsq[row] * (1.0f / DM) + 1e-6f) : 1.0f;
.LBB0_640:
	v_ashrrev_i32_e32 v49, 31, v48
	v_lshl_add_u64 v[50:51], v[48:49], 2, s[14:15]
	v_mov_b32_e32 v49, v245
	v_fmamk_f32 v49, v49, 0x3a800000, v147
	v_rsq_f32_e32 v52, v49
	s_cmp_lt_i32 s36, 9
	s_cbranch_scc0 .LBB0_636

;     __device__ __forceinline__ void operator()(const f32x4 (&acc)[2][2][4][2], const pg8::Unit& u, int wr, int wc, int fr_, int fq_) const {
;     ...
;                 for (int m = 0; m < 4; ++m) { const int row = u.pm * 256 + 128 * ai + 64 * wr + 16 * m + fr; const int b = row >> 13, s = row & 8191;
;                     const float rin = rsq ? __builtin_amdgcn_rsqf(rsq[row] * (1.0f / DM) + 1e-6f) : 1.0f;
.LBB0_670:
	v_ashrrev_i32_e32 v33, 31, v32
	v_lshl_add_u64 v[34:35], v[32:33], 2, s[14:15]
	v_mov_b32_e32 v33, v246
	v_fmamk_f32 v33, v33, 0x3a800000, v147
	v_rsq_f32_e32 v36, v33
	s_cmp_lt_i32 s36, 9
	s_cbranch_scc0 .LBB0_666

;     __device__ __forceinline__ void operator()(const f32x4 (&acc)[2][2][4][2], const pg8::Unit& u, int wr, int wc, int fr_, int fq_) const {
;     ...
;                 for (int m = 0; m < 4; ++m) { const int row = u.pm * 256 + 128 * ai + 64 * wr + 16 * m + fr; const int b = row >> 13, s = row & 8191;
;                     const float rin = rsq ? __builtin_amdgcn_rsqf(rsq[row] * (1.0f / DM) + 1e-6f) : 1.0f;
.LBB0_700:
	v_ashrrev_i32_e32 v17, 31, v16
	v_lshl_add_u64 v[18:19], v[16:17], 2, s[14:15]
	v_mov_b32_e32 v17, v247
	v_fmamk_f32 v17, v17, 0x3a800000, v147
	v_rsq_f32_e32 v20, v17
	s_cmp_lt_i32 s36, 9
	s_cbranch_scc0 .LBB0_696

; __device__ __forceinline__ float bf2f(unsigned v16) { return __uint_as_float(v16 << 16); }
; __global__ void __launch_bounds__(512, 2) hybrid_fwd(Params P) {
;     ...
;             if (bx < 128) { const int kv = bx >> 6, ks = (bx >> 4) & 3;
;                 pg8::Gemm g{(const bf16_t*)(ws + WS_B + (kv ? HB_VCR : HB_KCR) * MiB) + ks * 512, (const bf16_t*)(ws + WS_WC1) + (size_t)kv * 256 * 2048 + ks * 512, 4096, 256, 512, 1024, 2048};
;                 pg8::StaticOrder S; S.init(4096, 256, G, bx & 15);
;                 EpiStoreF32 E{(float*)(ws + WS_H) + (size_t)(kv * 4 + ks) * 4096 * 256};
;     ...
;                 pg8::gemm_phase<EpiStoreF32, pg8::StaticOrder, true, true>(lds, g, S, E, tid);
;     ...
;             } else {
;                 const bf16_t* mbk = (const bf16_t*)(ws + WS_B + HB_MBK * MiB); float* KMEAN = (float*)(ws + WS_SMALL + 4096);
;                 for (int item = (bx - 128) * 8 + wave; item < 512; item += (G - 128) * 8) { const int bh = item >> 5, n = item & 31;
;                     const bf16_t* kp = mbk + ((size_t)bh * SEQ + 256 * n) * 64 + lane; float a = 0.f;
; #pragma unroll 8
;                     for (int j = 0; j < 256; ++j) a += bf2f(kp[(size_t)j * 64]);
;                     KMEAN[(size_t)item * 64 + lane] = a * (1.0f / 256.0f); }
.LBB0_740:
	s_nop 0
	s_nop 0
	s_nop 0
	s_nop 0
	s_nop 0
	s_or_b64 exec, exec, s[4:5]
	v_readlane_b32 s4, v255, 17
	s_barrier
	s_mov_b64 s[6:7], s[58:59]
	s_mov_b32 s28, s69
	s_mov_b32 s10, s2
	v_mov_b32_e32 v8, v146
	s_cmpk_gt_i32 s10, 0x7f
	v_readfirstlane_b32 s8, v8
	s_mov_b64 s[4:5], -1
	s_cbranch_scc0 .LBB0_747
	s_ashr_i32 s4, s8, 6
	s_lshl_b32 s5, s10, 3
	s_add_i32 s4, s5, s4
	s_addk_i32 s4, 0xfc00
	s_cmpk_gt_i32 s4, 0x1ff
	s_cbranch_scc1 .LBB0_746
	v_and_b32_e32 v2, 63, v8
	v_lshlrev_b32_e32 v80, 2, v2
	v_lshl_add_u64 v[0:1], s[6:7], 0, v[80:81]
	s_mov_b64 s[8:9], 0x2401000
	v_lshlrev_b32_e32 v80, 1, v2
	v_lshl_add_u64 v[0:1], v[0:1], 0, s[8:9]
	s_lshl_b32 s11, s28, 3
	v_lshl_add_u64 v[2:3], s[6:7], 0, v[80:81]
	s_mov_b64 s[8:9], 0x17100200
	s_lshl_b32 s13, s28, 17
	s_addk_i32 s11, 0xfc00
	v_lshl_add_u64 v[2:3], v[2:3], 0, s[8:9]
	s_lshl_b32 s12, s4, 14
	s_add_i32 s13, s13, 0xff000000

; #define LAS __attribute__((address_space(3)))
; __device__ __forceinline__ float wave_max(float v) { v = fmaxf(v, __shfl_xor(v, 1)); v = fmaxf(v, __shfl_xor(v, 2)); v = fmaxf(v, __shfl_xor(v, 4)); v = fmaxf(v, __shfl_xor(v, 8)); v = fmaxf(v, __shfl_xor(v, 16)); v = fmaxf(v, __shfl_xor(v, 32)); return v; }
; #define INP(k) ({ int k_ = (k); LAUNDER_S(k_); (const float*)(const GAS float*)P.in[k_]; })
; __global__ void __launch_bounds__(512, 2) hybrid_fwd(Params P) {
;     ...
;             LAS unsigned* misc = (LAS unsigned*)(lds + ATT_MISC); LAS float* btab = (LAS float*)(lds + ATT_BT);
;             const float* rel_bias = INP(1);
;             __syncthreads();
;             if (wave == 0) { const float* mqn = INP(4) + L * 64; const float* mkn = INP(5) + L * 64; const float* nqn = INP(6) + L * 64; const float* nkn = INP(7) + L * 192;
;                 float gq = fmaxf(fabsf(mqn[lane]), fabsf(nqn[lane])); float gk = fmaxf(fmaxf(fabsf(mkn[lane]), fabsf(nkn[lane])), fmaxf(fabsf(nkn[64 + lane]), fabsf(nkn[128 + lane])));
;                 float bm = 0.f;
; #pragma unroll
;                 for (int i = 0; i < 6; ++i) bm = fmaxf(bm, fabsf(rel_bias[lane + 64 * i]));
;                 gq = wave_max(gq); gk = wave_max(gk); bm = wave_max(bm);
;                 if (lane == 0) ((LAS float*)misc)[2] = 8.0f * gq * gk + bm; }
.LBB0_794:
	s_nop 0
	s_nop 0
	s_nop 0
	s_nop 0
	s_nop 0
	s_nop 0
	s_or_b64 exec, exec, s[4:5]
	v_readlane_b32 s4, v255, 17
	s_mov_b64 s[6:7], s[58:59]
	s_mov_b32 s5, s69
	s_barrier
	s_mov_b32 s5, s2
	v_mov_b32_e32 v210, v146
	s_mov_b32 s8, 1
	s_ashr_i32 s9, s8, 31
	s_lshl_b64 s[8:9], s[8:9], 3
	s_add_u32 s8, s0, s8
	s_addc_u32 s9, s1, s9
	s_load_dwordx2 s[8:9], s[8:9], 0x0
	v_readfirstlane_b32 s5, v210
	s_cmp_lt_u32 s5, 64
	s_waitcnt lgkmcnt(0)
	s_barrier
	s_cbranch_scc0 .LBB0_798
	s_mov_b32 s10, 4
	s_ashr_i32 s11, s10, 31
	s_lshl_b64 s[10:11], s[10:11], 3
	s_add_u32 s10, s0, s10
	s_addc_u32 s11, s1, s11
	s_load_dwordx2 s[12:13], s[10:11], 0x0
	s_lshl_b32 s10, s4, 6
	s_ashr_i32 s11, s10, 31
	s_lshl_b64 s[10:11], s[10:11], 2
	s_mov_b32 s14, 5
	s_waitcnt lgkmcnt(0)
	s_add_u32 s12, s12, s10
	s_addc_u32 s13, s13, s11
	s_ashr_i32 s15, s14, 31
	s_lshl_b64 s[14:15], s[14:15], 3
	s_add_u32 s14, s0, s14
	s_addc_u32 s15, s1, s15
	s_load_dwordx2 s[14:15], s[14:15], 0x0
	s_mov_b32 s16, 6
	v_and_b32_e32 v0, 63, v210
	v_lshlrev_b32_e32 v1, 2, v0
	s_waitcnt lgkmcnt(0)
	s_add_u32 s18, s14, s10
	s_addc_u32 s19, s15, s11
	s_ashr_i32 s17, s16, 31
	s_lshl_b64 s[14:15], s[16:17], 3
	s_add_u32 s14, s0, s14
	s_addc_u32 s15, s1, s15
	s_load_dwordx2 s[14:15], s[14:15], 0x0
	s_mov_b32 s16, 7
	global_load_dword v2, v1, s[18:19]
	global_load_dword v3, v1, s[8:9]
	global_load_dword v4, v1, s[8:9] offset:256
	global_load_dword v5, v1, s[8:9] offset:512
	global_load_dword v6, v1, s[8:9] offset:768
	global_load_dword v7, v1, s[8:9] offset:1024
	global_load_dword v8, v1, s[8:9] offset:1280
	global_load_dword v9, v1, s[12:13]
	s_mul_i32 s12, s4, 0xc0
	s_waitcnt lgkmcnt(0)
	s_add_u32 s10, s14, s10
	s_addc_u32 s11, s15, s11
	s_ashr_i32 s17, s16, 31
	global_load_dword v10, v1, s[10:11]
	s_lshl_b64 s[10:11], s[16:17], 3
	s_add_u32 s10, s0, s10
	s_addc_u32 s11, s1, s11
	s_load_dwordx2 s[10:11], s[10:11], 0x0
	s_ashr_i32 s13, s12, 31
	s_lshl_b64 s[12:13], s[12:13], 2
	v_mbcnt_hi_u32_b32 v13, -1, v167
	v_and_b32_e32 v15, 64, v13
	s_waitcnt lgkmcnt(0)
	s_add_u32 s10, s10, s12
	s_addc_u32 s11, s11, s13
	global_load_dword v11, v1, s[10:11] offset:512
	global_load_dword v12, v1, s[10:11] offset:256
	s_nop 0
	global_load_dword v1, v1, s[10:11]
	v_xor_b32_e32 v14, 1, v13
	v_add_u32_e32 v15, 64, v15
	v_cmp_lt_i32_e32 vcc, v14, v15
	v_xor_b32_e32 v16, 2, v13
	v_xor_b32_e32 v17, 4, v13
	v_cndmask_b32_e32 v14, v13, v14, vcc
	v_lshlrev_b32_e32 v14, 2, v14
	v_cmp_lt_i32_e32 vcc, v16, v15
	v_xor_b32_e32 v18, 8, v13
	v_xor_b32_e32 v19, 16, v13
	v_cndmask_b32_e32 v16, v13, v16, vcc
	v_cmp_lt_i32_e32 vcc, v17, v15
	v_xor_b32_e32 v20, 32, v13
	s_waitcnt vmcnt(9)
	v_max3_f32 v3, |v3|, 0, |v4|
	v_cndmask_b32_e32 v17, v13, v17, vcc
	s_waitcnt vmcnt(7)
	v_max3_f32 v3, v3, |v5|, |v6|
	v_cmp_lt_i32_e32 vcc, v18, v15
	s_waitcnt vmcnt(5)
	v_max3_f32 v3, v3, |v7|, |v8|
	ds_bpermute_b32 v4, v14, v3
	v_cndmask_b32_e32 v18, v13, v18, vcc
	v_cmp_lt_i32_e32 vcc, v19, v15
	s_waitcnt vmcnt(4)
	v_max_f32_e64 v6, |v9|, |v9|
	v_lshlrev_b32_e32 v5, 2, v18
	s_waitcnt lgkmcnt(0)
	v_max_f32_e32 v4, v4, v4
	v_cndmask_b32_e32 v19, v13, v19, vcc
	v_cmp_lt_i32_e32 vcc, v20, v15
	v_lshlrev_b32_e32 v15, 2, v16
	v_max_f32_e32 v3, v3, v4
	ds_bpermute_b32 v4, v15, v3
	s_waitcnt vmcnt(3)
	v_max_f32_e64 v7, |v10|, |v10|
	v_max_f32_e32 v6, v6, v7
	ds_bpermute_b32 v7, v14, v6
	v_lshlrev_b32_e32 v16, 2, v17
	s_waitcnt lgkmcnt(1)
	v_max_f32_e32 v4, v4, v4
	v_max_f32_e32 v3, v3, v4
	s_waitcnt vmcnt(2)
	v_max_f32_e64 v4, |v11|, |v11|
	s_waitcnt vmcnt(1)
	v_max_f32_e64 v10, |v12|, |v12|
	v_max_f32_e32 v4, v10, v4
	s_waitcnt vmcnt(0)
	v_max3_f32 v1, |v2|, |v1|, v4
	ds_bpermute_b32 v2, v14, v1
	s_waitcnt lgkmcnt(1)
	v_max_f32_e32 v7, v7, v7
	v_max_f32_e32 v6, v6, v7
	ds_bpermute_b32 v7, v15, v6
	ds_bpermute_b32 v11, v16, v3
	s_waitcnt lgkmcnt(2)
	v_max_f32_e32 v2, v2, v2
	v_max_f32_e32 v1, v1, v2
	ds_bpermute_b32 v2, v15, v1
	s_waitcnt lgkmcnt(2)
	v_max_f32_e32 v4, v7, v7
	v_max_f32_e32 v4, v6, v4
	s_waitcnt lgkmcnt(1)
	v_max_f32_e32 v6, v11, v11
	ds_bpermute_b32 v7, v16, v4
	s_waitcnt lgkmcnt(1)
	v_max_f32_e32 v2, v2, v2
	v_max_f32_e32 v1, v1, v2
	v_max_f32_e32 v3, v3, v6
	ds_bpermute_b32 v2, v16, v1
	ds_bpermute_b32 v6, v5, v3
	s_waitcnt lgkmcnt(2)
	v_max_f32_e32 v7, v7, v7
	v_max_f32_e32 v4, v4, v7
	ds_bpermute_b32 v7, v5, v4
	s_waitcnt lgkmcnt(2)
	v_max_f32_e32 v2, v2, v2
	s_waitcnt lgkmcnt(1)
	v_max_f32_e32 v6, v6, v6
	v_max_f32_e32 v1, v1, v2
	v_lshlrev_b32_e32 v8, 2, v19
	v_max_f32_e32 v3, v3, v6
	ds_bpermute_b32 v2, v5, v1
	ds_bpermute_b32 v6, v8, v3
	s_waitcnt lgkmcnt(2)
	v_max_f32_e32 v5, v7, v7
	v_max_f32_e32 v4, v4, v5
	v_cndmask_b32_e32 v13, v13, v20, vcc
	s_waitcnt lgkmcnt(1)
	v_max_f32_e32 v2, v2, v2
	s_waitcnt lgkmcnt(0)
	v_max_f32_e32 v5, v6, v6
	ds_bpermute_b32 v6, v8, v4
	v_max_f32_e32 v2, v1, v2
	ds_bpermute_b32 v7, v8, v2
	v_max_f32_e32 v1, v3, v5
	v_lshlrev_b32_e32 v9, 2, v13
	s_waitcnt lgkmcnt(1)
	v_max_f32_e32 v3, v6, v6
	v_max_f32_e32 v3, v4, v3
	s_waitcnt lgkmcnt(0)
	v_max_f32_e32 v4, v7, v7
	v_max_f32_e32 v2, v2, v4
	ds_bpermute_b32 v5, v9, v3
	ds_bpermute_b32 v4, v9, v2
	ds_bpermute_b32 v6, v9, v1
	v_cmp_eq_u32_e32 vcc, 0, v0
	s_and_saveexec_b64 s[10:11], vcc
	s_cbranch_execz .LBB0_797
	s_waitcnt lgkmcnt(2)
	v_max_f32_e32 v0, v5, v5
	v_max_f32_e32 v3, v3, v3
	v_max_f32_e32 v0, v3, v0
	s_waitcnt lgkmcnt(1)
	v_max_f32_e32 v3, v4, v4
	v_max_f32_e32 v2, v2, v2
	v_max_f32_e32 v2, v2, v3
	s_waitcnt lgkmcnt(0)
	v_max_f32_e32 v3, v6, v6
	v_max_f32_e32 v1, v1, v1
	v_mul_f32_e32 v0, 0x41000000, v0
	v_max_f32_e32 v1, v1, v3
	v_fmac_f32_e32 v1, v0, v2
	ds_write_b32 v165, v1 offset:50696

; __global__ void __launch_bounds__(512, 2) hybrid_fwd(Params P) {
;     ...
;         { PHASE_BEGIN
;             for (int it = bx; it < 256; it += G)
;                 for (int i = 0; i < 4; ++i) { int tidu = tid; asm volatile("" : "+v"(tidu));
;                     branch_tile(lds, (const bf16_t*)(ws + WS_H), (const bf16_t*)(ws + WS_WBR), (const bf16_t*)(ws + WS_A), (bf16_t*)(ws + WS_B), it >> 1, 4 * (it & 1) + i, tidu); }
.LBB0_1085:
	s_nop 0
	s_or_b64 exec, exec, s[4:5]
	s_mov_b32 s4, s34
	s_barrier
	s_mov_b64 s[4:5], s[58:59]
	s_mov_b32 s16, s69
	s_mov_b32 s17, s2
	v_mov_b32_e32 v138, v146
	s_cmpk_gt_i32 s17, 0xff
	s_cbranch_scc1 .LBB0_1096
	s_add_u32 s18, s4, 0x3100000
	s_addc_u32 s19, s5, 0
	s_add_u32 s20, s4, 0xd00000
	s_addc_u32 s21, s5, 0
	s_add_u32 s6, s4, 0x7100000
	s_addc_u32 s7, s5, 0
	s_add_u32 s8, s4, 0x13100000
	s_addc_u32 s9, s5, 0
	s_branch .LBB0_1088
